# v65 + P0 prologue rms_row loop: second-pass gain loads read from a per-wave LDS image instead of one L2 round trip per chunk; bit-identical
# speedup vs baseline: 1.0079x; 1.0000x over previous
.LBB0_365:
	s_mov_b64 s[2:3], s[0:1]
	s_getreg_b32 s4, hwreg(HW_REG_HW_ID, 0, 6)
	s_lshl_b32 s4, s4, 2
	s_and_b32 s4, s4, 0xfc
	s_add_i32 s4, s4, 0
	s_add_i32 s4, s4, 0x20200
	s_waitcnt vmcnt(4)
	v_mov_b32_e32 v0, s4
	ds_read_b32 v0, v0
	s_mov_b32 s4, s64
	v_mbcnt_lo_u32_b32 v1, -1, 0
	v_mbcnt_hi_u32_b32 v1, -1, v1
	s_waitcnt lgkmcnt(0)
	v_readfirstlane_b32 s5, v0
	s_nop 1
	v_lshl_add_u32 v0, s5, 6, v1
	s_lshl_b32 s4, s4, 3
	v_readfirstlane_b32 s5, v0
	s_ashr_i32 s5, s5, 6
	s_add_i32 s10, s4, s5
	s_cmpk_gt_i32 s10, 0x3fff
	s_cbranch_scc1 .LBB0_368
	v_mbcnt_lo_u32_b32 v1, -1, 0
	v_mbcnt_hi_u32_b32 v1, -1, v1
	v_and_b32_e32 v2, 64, v1
	v_add_u32_e32 v2, 64, v2
	v_xor_b32_e32 v3, 1, v1
	v_cmp_lt_i32_e32 vcc, v3, v2
	s_load_dword s11, s[8:9], 0x10
	s_load_dword s12, s[8:9], 0x0
	s_load_dwordx2 s[14:15], s[2:3], 0x90
	s_load_dwordx4 s[4:7], s[2:3], 0x0
	v_cndmask_b32_e32 v3, v1, v3, vcc
	v_lshlrev_b32_e32 v117, 2, v3
	v_xor_b32_e32 v3, 2, v1
	v_cmp_lt_i32_e32 vcc, v3, v2
	s_waitcnt lgkmcnt(0)
	s_lshr_b32 s2, s11, 16
	s_cmp_lg_u32 s2, 0
	v_cndmask_b32_e32 v3, v1, v3, vcc
	v_lshlrev_b32_e32 v119, 2, v3
	v_xor_b32_e32 v3, 4, v1
	v_cmp_lt_i32_e32 vcc, v3, v2
	s_cselect_b64 s[2:3], -1, 0
	s_cmp_lg_u64 s[2:3], 0
	v_cndmask_b32_e32 v3, v1, v3, vcc
	v_lshlrev_b32_e32 v123, 2, v3
	v_xor_b32_e32 v3, 8, v1
	v_cmp_lt_i32_e32 vcc, v3, v2
	s_addc_u32 s2, s12, 0
	s_lshl_b32 s12, s2, 3
	v_cndmask_b32_e32 v3, v1, v3, vcc
	v_lshlrev_b32_e32 v125, 2, v3
	v_xor_b32_e32 v3, 16, v1
	v_cmp_lt_i32_e32 vcc, v3, v2
	s_mov_b64 s[2:3], 0x1000
	s_ashr_i32 s11, s10, 31
	v_cndmask_b32_e32 v3, v1, v3, vcc
	v_lshlrev_b32_e32 v127, 2, v3
	v_xor_b32_e32 v3, 32, v1
	v_cmp_lt_i32_e32 vcc, v3, v2
	v_and_b32_e32 v4, 63, v0
	v_mov_b32_e32 v136, 0x358637bd
	v_cndmask_b32_e32 v1, v1, v3, vcc
	v_lshlrev_b32_e32 v129, 2, v1
	v_lshlrev_b32_e32 v1, 4, v0
	v_and_b32_e32 v2, 0x3f0, v1
	v_mov_b32_e32 v3, 0
	v_lshl_add_u64 v[68:69], s[6:7], 0, v[2:3]
	v_lshl_add_u64 v[70:71], v[68:69], 0, s[2:3]
	s_mov_b64 s[2:3], 0x1400
	v_lshl_add_u64 v[72:73], v[68:69], 0, s[2:3]
	s_mov_b64 s[2:3], 0x1800
	v_lshl_add_u64 v[74:75], v[68:69], 0, s[2:3]
	s_mov_b64 s[2:3], 0x1c00
	v_lshl_add_u64 v[76:77], v[68:69], 0, s[2:3]
	s_mov_b64 s[2:3], 0x2000
	s_lshl_b64 s[6:7], s[10:11], 13
	v_lshl_add_u64 v[78:79], v[68:69], 0, s[2:3]
	s_mov_b64 s[2:3], 0x2400
	s_add_u32 s6, s14, s6
	v_lshl_add_u64 v[80:81], v[68:69], 0, s[2:3]
	s_mov_b64 s[2:3], 0x2800
	v_lshlrev_b32_e32 v2, 3, v4
	s_addc_u32 s7, s15, s7
	v_lshl_add_u64 v[82:83], v[68:69], 0, s[2:3]
	s_mov_b64 s[2:3], 0x2c00
	v_lshl_add_u64 v[0:1], s[6:7], 0, v[2:3]
	s_mov_b64 s[6:7], 0x1a001e00
	s_ashr_i32 s13, s12, 31
	v_lshl_add_u64 v[84:85], v[68:69], 0, s[2:3]
	s_mov_b64 s[2:3], 0x3000
	v_lshl_add_u64 v[94:95], v[0:1], 0, s[6:7]
	s_lshl_b64 s[6:7], s[12:13], 13
	s_lshl_b64 s[14:15], s[10:11], 14
	v_lshl_add_u64 v[86:87], v[68:69], 0, s[2:3]
	s_mov_b64 s[2:3], 0x3400
	s_add_u32 s4, s4, s14
	v_lshl_add_u64 v[88:89], v[68:69], 0, s[2:3]
	s_mov_b64 s[2:3], 0x3800
	v_lshlrev_b32_e32 v2, 4, v4
	s_addc_u32 s5, s5, s15
	v_lshl_add_u64 v[90:91], v[68:69], 0, s[2:3]
	s_mov_b64 s[2:3], 0x3c00
	v_lshl_add_u64 v[0:1], s[4:5], 0, v[2:3]
	v_lshl_add_u64 v[92:93], v[68:69], 0, s[2:3]
	v_lshl_add_u64 v[96:97], v[0:1], 0, s[2:3]
	s_lshl_b64 s[4:5], s[12:13], 14
	s_movk_i32 s11, 0xe000
	s_movk_i32 s13, 0xf000
	s_mov_b32 s14, 0xf800000
	v_mov_b32_e32 v137, 0x260
	s_movk_i32 s15, 0x7fff
	v_mov_b32_e32 v138, 1
	s_and_b32 s80, s10, 7
	s_lshl_b32 s80, s80, 14
	v_mbcnt_lo_u32_b32 v240, -1, 0
	v_mbcnt_hi_u32_b32 v240, -1, v240
	v_lshlrev_b32_e32 v240, 4, v240
	v_add_u32_e32 v240, s80, v240
	global_load_dwordx4 v[200:203], v[68:69], off
	global_load_dwordx4 v[204:207], v[68:69], off offset:1024
	global_load_dwordx4 v[208:211], v[68:69], off offset:2048
	global_load_dwordx4 v[212:215], v[68:69], off offset:3072
	global_load_dwordx4 v[216:219], v[70:71], off
	global_load_dwordx4 v[220:223], v[72:73], off
	global_load_dwordx4 v[224:227], v[74:75], off
	global_load_dwordx4 v[228:231], v[76:77], off
	s_waitcnt vmcnt(0)
	ds_write_b128 v240, v[200:203] offset:0
	ds_write_b128 v240, v[204:207] offset:1024
	ds_write_b128 v240, v[208:211] offset:2048
	ds_write_b128 v240, v[212:215] offset:3072
	ds_write_b128 v240, v[216:219] offset:4096
	ds_write_b128 v240, v[220:223] offset:5120
	ds_write_b128 v240, v[224:227] offset:6144
	ds_write_b128 v240, v[228:231] offset:7168
	global_load_dwordx4 v[200:203], v[78:79], off
	global_load_dwordx4 v[204:207], v[80:81], off
	global_load_dwordx4 v[208:211], v[82:83], off
	global_load_dwordx4 v[212:215], v[84:85], off
	global_load_dwordx4 v[216:219], v[86:87], off
	global_load_dwordx4 v[220:223], v[88:89], off
	global_load_dwordx4 v[224:227], v[90:91], off
	global_load_dwordx4 v[228:231], v[92:93], off
	s_waitcnt vmcnt(0)
	ds_write_b128 v240, v[200:203] offset:8192
	ds_write_b128 v240, v[204:207] offset:9216
	ds_write_b128 v240, v[208:211] offset:10240
	ds_write_b128 v240, v[212:215] offset:11264
	ds_write_b128 v240, v[216:219] offset:12288
	ds_write_b128 v240, v[220:223] offset:13312
	ds_write_b128 v240, v[224:227] offset:14336
	ds_write_b128 v240, v[228:231] offset:15360
	s_waitcnt lgkmcnt(0)
.LBB0_367:
	v_add_co_u32_e64 v52, s[2:3], s11, v96
	v_add_co_u32_e32 v100, vcc, 0xffffd000, v96
	s_nop 0
	v_addc_co_u32_e64 v53, s[2:3], -1, v97, s[2:3]
	v_add_co_u32_e64 v54, s[2:3], s13, v96
	v_addc_co_u32_e32 v101, vcc, -1, v97, vcc
	s_nop 0
	v_addc_co_u32_e64 v55, s[2:3], -1, v97, s[2:3]
	global_load_dwordx4 v[12:15], v[96:97], off offset:-3072
	global_load_dwordx4 v[8:11], v[96:97], off offset:-2048
	global_load_dwordx4 v[4:7], v[96:97], off offset:-1024
	global_load_dwordx4 v[0:3], v[96:97], off
	global_load_dwordx4 v[28:31], v[68:69], off
	global_load_dwordx4 v[44:47], v[52:53], off offset:-3072
	global_load_dwordx4 v[32:35], v[52:53], off offset:-1024
	global_load_dwordx4 v[48:51], v[52:53], off offset:-2048
	global_load_dwordx4 v[36:39], v[52:53], off
	global_load_dwordx4 v[24:27], v[54:55], off offset:-2048
	global_load_dwordx4 v[40:43], v[54:55], off offset:-3072
	global_load_dwordx4 v[20:23], v[54:55], off offset:-1024
	global_load_dwordx4 v[16:19], v[96:97], off offset:-4096
	global_load_dwordx4 v[64:67], v[100:101], off offset:-3072
	global_load_dwordx4 v[56:59], v[100:101], off offset:-2048
	s_nop 0
	global_load_dwordx4 v[52:55], v[100:101], off
	global_load_dwordx4 v[60:63], v[100:101], off offset:-1024
	v_add_co_u32_e64 v98, s[2:3], s13, v94
	s_add_i32 s10, s10, s12
	s_nop 0
	v_addc_co_u32_e64 v99, s[2:3], -1, v95, s[2:3]
	v_lshl_add_u64 v[96:97], v[96:97], 0, s[4:5]
	s_cmpk_lt_i32 s10, 0x4000
	s_waitcnt vmcnt(11)
	v_pk_mul_f32 v[112:113], v[46:47], v[46:47]
	s_waitcnt vmcnt(10)
	v_mul_f32_e32 v142, v32, v32
	v_mul_f32_e32 v145, v33, v33
	s_waitcnt vmcnt(8)
	v_pk_mul_f32 v[114:115], v[38:39], v[38:39]
	v_pk_mul_f32 v[102:103], v[36:37], v[36:37]
	s_waitcnt vmcnt(7)
	v_mul_f32_e32 v144, v24, v24
	v_mul_f32_e32 v148, v25, v25
	v_mul_f32_e32 v151, v26, v26
	s_waitcnt vmcnt(6)
	v_mul_f32_e32 v122, v41, v41
	v_mul_f32_e32 v124, v43, v43
	v_mov_b32_e32 v156, v24
	v_mov_b32_e32 v157, v26
	v_mov_b32_e32 v26, v25
	s_waitcnt vmcnt(3)
	v_pk_mul_f32 v[24:25], v[66:67], v[66:67]
	v_pk_mul_f32 v[158:159], v[64:65], v[64:65]
	s_waitcnt vmcnt(2)
	v_pk_mul_f32 v[160:161], v[58:59], v[58:59]
	v_pk_mul_f32 v[162:163], v[56:57], v[56:57]
	v_pk_mul_f32 v[106:107], v[10:11], v[10:11]
	v_pk_mul_f32 v[108:109], v[8:9], v[8:9]
	v_mul_f32_e32 v110, v5, v5
	v_mul_f32_e32 v132, v7, v7
	v_mul_f32_e32 v149, v34, v34
	v_mov_b32_e32 v134, v32
	v_mov_b32_e32 v135, v34
	v_mov_b32_e32 v34, v33
	v_mov_b32_e32 v32, v36
	v_mov_b32_e32 v33, v38
	v_mov_b32_e32 v38, v37
	v_mov_b32_e32 v36, v40
	v_mov_b32_e32 v37, v42
	v_pk_mov_b32 v[172:173], v[102:103], v[114:115] op_sel:[1,0]
	v_mov_b32_e32 v103, v115
	v_pk_fma_f32 v[114:115], v[40:41], v[40:41], v[122:123] op_sel_hi:[1,1,0]
	v_pk_fma_f32 v[174:175], v[42:43], v[42:43], v[124:125] op_sel_hi:[1,1,0]
	v_mov_b32_e32 v42, v41
	v_pk_mov_b32 v[40:41], v[158:159], v[24:25] op_sel:[1,0]
	v_mov_b32_e32 v159, v25
	v_pk_mov_b32 v[24:25], v[162:163], v[160:161] op_sel:[1,0]
	v_mov_b32_e32 v163, v161
	v_mul_f32_e32 v154, v3, v3
	v_mov_b32_e32 v100, v28
	v_mov_b32_e32 v101, v30
	v_mov_b32_e32 v30, v29
	v_pk_mul_f32 v[28:29], v[44:45], v[44:45]
	v_mul_f32_e32 v116, v49, v49
	v_mul_f32_e32 v118, v51, v51
	v_pk_mov_b32 v[130:131], v[108:109], v[106:107] op_sel:[1,0]
	v_mov_b32_e32 v109, v107
	v_pk_fma_f32 v[106:107], v[4:5], v[4:5], v[110:111] op_sel_hi:[1,1,0]
	v_pk_fma_f32 v[110:111], v[6:7], v[6:7], v[132:133] op_sel_hi:[1,1,0]
	s_waitcnt vmcnt(1)
	v_mul_f32_e32 v165, v52, v52
	v_mul_f32_e32 v167, v53, v53
	s_waitcnt vmcnt(0)
	v_mul_f32_e32 v164, v61, v61
	v_mul_f32_e32 v166, v63, v63
	v_pk_add_f32 v[40:41], v[40:41], v[158:159]
	v_pk_add_f32 v[24:25], v[24:25], v[162:163]
	v_mov_b32_e32 v132, v44
	v_mov_b32_e32 v133, v46
	v_mov_b32_e32 v46, v45
	v_mov_b32_e32 v44, v48
	v_mov_b32_e32 v45, v50
	v_mul_f32_e32 v180, v54, v54
	v_mul_f32_e32 v181, v55, v55
	v_pk_mov_b32 v[168:169], v[28:29], v[112:113] op_sel:[1,0]
	v_mov_b32_e32 v29, v113
	v_pk_fma_f32 v[112:113], v[48:49], v[48:49], v[116:117] op_sel_hi:[1,1,0]
	v_pk_fma_f32 v[170:171], v[50:51], v[50:51], v[118:119] op_sel_hi:[1,1,0]
	v_mov_b32_e32 v111, v154
	v_mov_b32_e32 v154, v52
	v_mov_b32_e32 v155, v54
	v_mov_b32_e32 v54, v53
	v_mov_b32_e32 v50, v49
	v_pk_fma_f32 v[48:49], v[60:61], v[60:61], v[164:165] op_sel_hi:[1,1,0]
	v_pk_fma_f32 v[52:53], v[62:63], v[62:63], v[166:167] op_sel_hi:[1,1,0]
	v_pk_add_f32 v[40:41], v[40:41], v[40:41] op_sel:[0,1] op_sel_hi:[1,0]
	v_pk_add_f32 v[24:25], v[24:25], v[24:25] op_sel:[0,1] op_sel_hi:[1,0]
	v_mov_b32_e32 v49, v180
	v_mov_b32_e32 v53, v181
	v_mov_b32_e32 v41, v165
	v_mov_b32_e32 v25, v167
	v_pk_add_f32 v[48:49], v[48:49], v[52:53]
	v_pk_add_f32 v[24:25], v[40:41], v[24:25]
	v_pk_add_f32 v[28:29], v[168:169], v[28:29]
	v_pk_add_f32 v[24:25], v[24:25], v[48:49]
	v_mul_f32_e32 v150, v35, v35
	v_pk_add_f32 v[28:29], v[28:29], v[28:29] op_sel:[0,1] op_sel_hi:[1,0]
	v_pk_add_f32 v[24:25], v[24:25], v[24:25] op_sel:[0,1] op_sel_hi:[1,0]
	v_mov_b32_e32 v113, v149
	v_mov_b32_e32 v171, v150
	v_mov_b32_e32 v29, v145
	v_mov_b32_e32 v25, v142
	v_pk_add_f32 v[108:109], v[130:131], v[108:109]
	v_mov_b32_e32 v130, v64
	v_mov_b32_e32 v131, v66
	v_mov_b32_e32 v66, v65
	v_mov_b32_e32 v64, v56
	v_mov_b32_e32 v65, v58
	v_mov_b32_e32 v58, v57
	v_mov_b32_e32 v56, v60
	v_mov_b32_e32 v57, v62
	v_mov_b32_e32 v62, v61
	v_pk_add_f32 v[60:61], v[112:113], v[170:171]
	v_pk_add_f32 v[24:25], v[24:25], v[28:29]
	v_pk_add_f32 v[102:103], v[172:173], v[102:103]
	v_pk_add_f32 v[24:25], v[24:25], v[60:61]
	v_mul_f32_e32 v153, v2, v2
	v_mul_f32_e32 v152, v27, v27
	v_pk_add_f32 v[102:103], v[102:103], v[102:103] op_sel:[0,1] op_sel_hi:[1,0]
	v_pk_add_f32 v[24:25], v[24:25], v[24:25] op_sel:[0,1] op_sel_hi:[1,0]
	v_pk_mul_f32 v[120:121], v[22:23], v[22:23]
	v_pk_mul_f32 v[104:105], v[20:21], v[20:21]
	v_mov_b32_e32 v107, v153
	v_mov_b32_e32 v115, v151
	v_mov_b32_e32 v175, v152
	v_mov_b32_e32 v103, v148
	v_mov_b32_e32 v25, v144
	v_pk_mov_b32 v[176:177], v[104:105], v[120:121] op_sel:[1,0]
	v_mov_b32_e32 v105, v121
	v_pk_add_f32 v[106:107], v[106:107], v[110:111]
	v_pk_add_f32 v[110:111], v[114:115], v[174:175]
	v_pk_add_f32 v[24:25], v[24:25], v[102:103]
	v_mul_f32_e32 v126, v17, v17
	v_mul_f32_e32 v128, v19, v19
	v_pk_add_f32 v[104:105], v[176:177], v[104:105]
	v_pk_add_f32 v[24:25], v[24:25], v[110:111]
	v_mul_f32_e32 v139, v12, v12
	v_mul_f32_e32 v141, v13, v13
	v_mul_f32_e32 v146, v14, v14
	v_mul_f32_e32 v147, v15, v15
	v_pk_fma_f32 v[120:121], v[16:17], v[16:17], v[126:127] op_sel_hi:[1,1,0]
	v_pk_fma_f32 v[178:179], v[18:19], v[18:19], v[128:129] op_sel_hi:[1,1,0]
	v_pk_add_f32 v[104:105], v[104:105], v[104:105] op_sel:[0,1] op_sel_hi:[1,0]
	v_pk_add_f32 v[24:25], v[24:25], v[24:25] op_sel:[0,1] op_sel_hi:[1,0]
	v_mov_b32_e32 v121, v146
	v_mov_b32_e32 v179, v147
	v_mov_b32_e32 v105, v141
	v_mov_b32_e32 v25, v139
	v_pk_add_f32 v[112:113], v[120:121], v[178:179]
	v_pk_add_f32 v[24:25], v[24:25], v[104:105]
	v_mul_f32_e32 v140, v0, v0
	v_pk_add_f32 v[24:25], v[24:25], v[112:113]
	v_mul_f32_e32 v143, v1, v1
	v_pk_add_f32 v[108:109], v[108:109], v[108:109] op_sel:[0,1] op_sel_hi:[1,0]
	v_pk_add_f32 v[24:25], v[24:25], v[24:25] op_sel:[0,1] op_sel_hi:[1,0]
	v_mov_b32_e32 v109, v143
	v_mov_b32_e32 v25, v140
	v_pk_add_f32 v[24:25], v[24:25], v[108:109]
	s_nop 0
	v_pk_add_f32 v[24:25], v[24:25], v[106:107]
	s_nop 0
	v_add_f32_e32 v24, v24, v25
	ds_bpermute_b32 v25, v117, v24
	s_waitcnt lgkmcnt(0)
	v_add_f32_e32 v24, v24, v25
	ds_bpermute_b32 v25, v119, v24
	s_waitcnt lgkmcnt(0)
	v_add_f32_e32 v24, v24, v25
	ds_bpermute_b32 v25, v123, v24
	s_waitcnt lgkmcnt(0)
	v_add_f32_e32 v24, v24, v25
	ds_bpermute_b32 v25, v125, v24
	s_waitcnt lgkmcnt(0)
	v_add_f32_e32 v24, v24, v25
	ds_bpermute_b32 v25, v127, v24
	s_waitcnt lgkmcnt(0)
	v_add_f32_e32 v24, v24, v25
	ds_bpermute_b32 v25, v129, v24
	s_waitcnt lgkmcnt(0)
	v_add_f32_e32 v24, v24, v25
	v_fmamk_f32 v24, v24, 0x39800000, v136
	v_mul_f32_e32 v25, 0x4f800000, v24
	v_cmp_gt_f32_e32 vcc, s14, v24
	s_nop 1
	v_cndmask_b32_e32 v24, v24, v25, vcc
	v_sqrt_f32_e32 v25, v24
	s_nop 0
	v_add_u32_e32 v28, -1, v25
	v_add_u32_e32 v29, 1, v25
	v_fma_f32 v40, -v28, v25, v24
	v_fma_f32 v41, -v29, v25, v24
	v_cmp_ge_f32_e64 s[2:3], 0, v40
	s_nop 1
	v_cndmask_b32_e64 v25, v25, v28, s[2:3]
	v_cmp_lt_f32_e64 s[2:3], 0, v41
	s_nop 1
	v_cndmask_b32_e64 v25, v25, v29, s[2:3]
	v_mul_f32_e32 v28, 0x37800000, v25
	v_cndmask_b32_e32 v25, v25, v28, vcc
	v_cmp_class_f32_e32 vcc, v24, v137
	s_nop 1
	v_cndmask_b32_e32 v24, v25, v24, vcc
	v_div_scale_f32 v25, s[2:3], v24, v24, 1.0
	v_rcp_f32_e32 v29, v25
	v_div_scale_f32 v28, vcc, 1.0, v24, 1.0
	v_fma_f32 v40, -v25, v29, 1.0
	v_fmac_f32_e32 v29, v40, v29
	v_mul_f32_e32 v40, v28, v29
	v_fma_f32 v41, -v25, v40, v28
	v_fmac_f32_e32 v40, v41, v29
	v_fma_f32 v25, -v25, v40, v28
	v_div_fmas_f32 v25, v25, v29, v40
	v_div_fixup_f32 v24, v25, v24, 1.0
	v_pk_mul_f32 v[48:49], v[66:67], v[24:25] op_sel_hi:[1,0]
	v_pk_mul_f32 v[40:41], v[130:131], v[24:25] op_sel_hi:[1,0]
	v_pk_mul_f32 v[30:31], v[30:31], v[48:49]
	v_pk_mul_f32 v[102:103], v[32:33], v[24:25] op_sel_hi:[1,0]
	v_pk_mul_f32 v[32:33], v[100:101], v[40:41]
	v_and_b32_sdwa v41, v31, v138 dst_sel:DWORD dst_unused:UNUSED_PAD src0_sel:WORD_1 src1_sel:DWORD
	v_and_b32_sdwa v48, v30, v138 dst_sel:DWORD dst_unused:UNUSED_PAD src0_sel:WORD_1 src1_sel:DWORD
	v_pk_mul_f32 v[52:53], v[64:65], v[24:25] op_sel_hi:[1,0]
	v_pk_mul_f32 v[58:59], v[58:59], v[24:25] op_sel_hi:[1,0]
	v_pk_mul_f32 v[56:57], v[56:57], v[24:25] op_sel_hi:[1,0]
	v_pk_mul_f32 v[60:61], v[62:63], v[24:25] op_sel_hi:[1,0]
	v_pk_mul_f32 v[62:63], v[154:155], v[24:25] op_sel_hi:[1,0]
	v_pk_mul_f32 v[54:55], v[54:55], v[24:25] op_sel_hi:[1,0]
	v_pk_mul_f32 v[64:65], v[132:133], v[24:25] op_sel_hi:[1,0]
	v_pk_mul_f32 v[46:47], v[46:47], v[24:25] op_sel_hi:[1,0]
	v_pk_mul_f32 v[44:45], v[44:45], v[24:25] op_sel_hi:[1,0]
	v_pk_mul_f32 v[50:51], v[50:51], v[24:25] op_sel_hi:[1,0]
	v_pk_mul_f32 v[66:67], v[134:135], v[24:25] op_sel_hi:[1,0]
	v_pk_mul_f32 v[34:35], v[34:35], v[24:25] op_sel_hi:[1,0]
	v_pk_mul_f32 v[38:39], v[38:39], v[24:25] op_sel_hi:[1,0]
	v_pk_mul_f32 v[36:37], v[36:37], v[24:25] op_sel_hi:[1,0]
	v_pk_mul_f32 v[42:43], v[42:43], v[24:25] op_sel_hi:[1,0]
	v_pk_mul_f32 v[28:29], v[156:157], v[24:25] op_sel_hi:[1,0]
	v_and_b32_sdwa v25, v33, v138 dst_sel:DWORD dst_unused:UNUSED_PAD src0_sel:WORD_1 src1_sel:DWORD
	v_and_b32_sdwa v40, v32, v138 dst_sel:DWORD dst_unused:UNUSED_PAD src0_sel:WORD_1 src1_sel:DWORD
	v_add3_u32 v31, v31, v41, s15
	v_add3_u32 v30, v30, v48, s15
	v_add3_u32 v32, v32, v40, s15
	v_add3_u32 v25, v33, v25, s15
	v_and_b32_e32 v31, 0xffff0000, v31
	v_and_b32_e32 v30, 0xffff0000, v30
	v_or_b32_sdwa v31, v31, v25 dst_sel:DWORD dst_unused:UNUSED_PAD src0_sel:DWORD src1_sel:WORD_1
	v_or_b32_sdwa v30, v30, v32 dst_sel:DWORD dst_unused:UNUSED_PAD src0_sel:DWORD src1_sel:WORD_1
	global_store_dwordx2 v[98:99], v[30:31], off offset:-3584
	ds_read_b128 v[30:33], v240 offset:1024
	s_waitcnt lgkmcnt(0)
	v_mov_b32_e32 v40, v30
	v_mov_b32_e32 v41, v32
	v_mov_b32_e32 v32, v31
	v_pk_mul_f32 v[30:31], v[40:41], v[52:53]
	v_pk_mul_f32 v[32:33], v[32:33], v[58:59]
	v_and_b32_sdwa v25, v31, v138 dst_sel:DWORD dst_unused:UNUSED_PAD src0_sel:WORD_1 src1_sel:DWORD
	v_and_b32_sdwa v41, v33, v138 dst_sel:DWORD dst_unused:UNUSED_PAD src0_sel:WORD_1 src1_sel:DWORD
	v_and_b32_sdwa v48, v32, v138 dst_sel:DWORD dst_unused:UNUSED_PAD src0_sel:WORD_1 src1_sel:DWORD
	v_and_b32_sdwa v40, v30, v138 dst_sel:DWORD dst_unused:UNUSED_PAD src0_sel:WORD_1 src1_sel:DWORD
	v_add3_u32 v25, v31, v25, s15
	v_add3_u32 v31, v33, v41, s15
	v_add3_u32 v32, v32, v48, s15
	v_add3_u32 v30, v30, v40, s15
	v_and_b32_e32 v31, 0xffff0000, v31
	v_and_b32_e32 v32, 0xffff0000, v32
	v_or_b32_sdwa v31, v31, v25 dst_sel:DWORD dst_unused:UNUSED_PAD src0_sel:DWORD src1_sel:WORD_1
	v_or_b32_sdwa v30, v32, v30 dst_sel:DWORD dst_unused:UNUSED_PAD src0_sel:DWORD src1_sel:WORD_1
	global_store_dwordx2 v[98:99], v[30:31], off offset:-3072
	ds_read_b128 v[30:33], v240 offset:2048
	s_waitcnt lgkmcnt(0)
	v_mov_b32_e32 v40, v30
	v_mov_b32_e32 v41, v32
	v_mov_b32_e32 v32, v31
	v_pk_mul_f32 v[30:31], v[40:41], v[56:57]
	v_pk_mul_f32 v[32:33], v[32:33], v[60:61]
	v_and_b32_sdwa v25, v31, v138 dst_sel:DWORD dst_unused:UNUSED_PAD src0_sel:WORD_1 src1_sel:DWORD
	v_and_b32_sdwa v41, v33, v138 dst_sel:DWORD dst_unused:UNUSED_PAD src0_sel:WORD_1 src1_sel:DWORD
	v_and_b32_sdwa v48, v32, v138 dst_sel:DWORD dst_unused:UNUSED_PAD src0_sel:WORD_1 src1_sel:DWORD
	v_and_b32_sdwa v40, v30, v138 dst_sel:DWORD dst_unused:UNUSED_PAD src0_sel:WORD_1 src1_sel:DWORD
	v_add3_u32 v25, v31, v25, s15
	v_add3_u32 v31, v33, v41, s15
	v_add3_u32 v32, v32, v48, s15
	v_add3_u32 v30, v30, v40, s15
	v_and_b32_e32 v31, 0xffff0000, v31
	v_and_b32_e32 v32, 0xffff0000, v32
	v_or_b32_sdwa v31, v31, v25 dst_sel:DWORD dst_unused:UNUSED_PAD src0_sel:DWORD src1_sel:WORD_1
	v_or_b32_sdwa v30, v32, v30 dst_sel:DWORD dst_unused:UNUSED_PAD src0_sel:DWORD src1_sel:WORD_1
	global_store_dwordx2 v[98:99], v[30:31], off offset:-2560
	ds_read_b128 v[30:33], v240 offset:3072
	s_waitcnt lgkmcnt(0)
	v_mov_b32_e32 v40, v30
	v_mov_b32_e32 v41, v32
	v_mov_b32_e32 v32, v31
	v_pk_mul_f32 v[30:31], v[40:41], v[62:63]
	v_pk_mul_f32 v[32:33], v[32:33], v[54:55]
	v_and_b32_sdwa v25, v31, v138 dst_sel:DWORD dst_unused:UNUSED_PAD src0_sel:WORD_1 src1_sel:DWORD
	v_and_b32_sdwa v41, v33, v138 dst_sel:DWORD dst_unused:UNUSED_PAD src0_sel:WORD_1 src1_sel:DWORD
	v_and_b32_sdwa v48, v32, v138 dst_sel:DWORD dst_unused:UNUSED_PAD src0_sel:WORD_1 src1_sel:DWORD
	v_and_b32_sdwa v40, v30, v138 dst_sel:DWORD dst_unused:UNUSED_PAD src0_sel:WORD_1 src1_sel:DWORD
	v_add3_u32 v25, v31, v25, s15
	v_add3_u32 v31, v33, v41, s15
	v_add3_u32 v32, v32, v48, s15
	v_add3_u32 v30, v30, v40, s15
	v_and_b32_e32 v31, 0xffff0000, v31
	v_and_b32_e32 v32, 0xffff0000, v32
	v_or_b32_sdwa v31, v31, v25 dst_sel:DWORD dst_unused:UNUSED_PAD src0_sel:DWORD src1_sel:WORD_1
	v_or_b32_sdwa v30, v32, v30 dst_sel:DWORD dst_unused:UNUSED_PAD src0_sel:DWORD src1_sel:WORD_1
	global_store_dwordx2 v[98:99], v[30:31], off offset:-2048
	ds_read_b128 v[30:33], v240 offset:4096
	s_waitcnt lgkmcnt(0)
	v_mov_b32_e32 v40, v30
	v_mov_b32_e32 v41, v32
	v_mov_b32_e32 v32, v31
	v_pk_mul_f32 v[30:31], v[64:65], v[40:41]
	v_pk_mul_f32 v[32:33], v[46:47], v[32:33]
	v_and_b32_sdwa v25, v31, v138 dst_sel:DWORD dst_unused:UNUSED_PAD src0_sel:WORD_1 src1_sel:DWORD
	v_and_b32_sdwa v41, v33, v138 dst_sel:DWORD dst_unused:UNUSED_PAD src0_sel:WORD_1 src1_sel:DWORD
	v_and_b32_sdwa v46, v32, v138 dst_sel:DWORD dst_unused:UNUSED_PAD src0_sel:WORD_1 src1_sel:DWORD
	v_and_b32_sdwa v40, v30, v138 dst_sel:DWORD dst_unused:UNUSED_PAD src0_sel:WORD_1 src1_sel:DWORD
	v_add3_u32 v25, v31, v25, s15
	v_add3_u32 v31, v33, v41, s15
	v_add3_u32 v32, v32, v46, s15
	v_add3_u32 v30, v30, v40, s15
	v_and_b32_e32 v31, 0xffff0000, v31
	v_and_b32_e32 v32, 0xffff0000, v32
	v_or_b32_sdwa v31, v31, v25 dst_sel:DWORD dst_unused:UNUSED_PAD src0_sel:DWORD src1_sel:WORD_1
	v_or_b32_sdwa v30, v32, v30 dst_sel:DWORD dst_unused:UNUSED_PAD src0_sel:DWORD src1_sel:WORD_1
	global_store_dwordx2 v[98:99], v[30:31], off offset:-1536
	ds_read_b128 v[30:33], v240 offset:5120
	s_waitcnt lgkmcnt(0)
	v_mov_b32_e32 v40, v30
	v_mov_b32_e32 v41, v32
	v_mov_b32_e32 v32, v31
	v_pk_mul_f32 v[30:31], v[44:45], v[40:41]
	v_pk_mul_f32 v[32:33], v[50:51], v[32:33]
	v_and_b32_sdwa v25, v31, v138 dst_sel:DWORD dst_unused:UNUSED_PAD src0_sel:WORD_1 src1_sel:DWORD
	v_and_b32_sdwa v41, v33, v138 dst_sel:DWORD dst_unused:UNUSED_PAD src0_sel:WORD_1 src1_sel:DWORD
	v_and_b32_sdwa v44, v32, v138 dst_sel:DWORD dst_unused:UNUSED_PAD src0_sel:WORD_1 src1_sel:DWORD
	v_and_b32_sdwa v40, v30, v138 dst_sel:DWORD dst_unused:UNUSED_PAD src0_sel:WORD_1 src1_sel:DWORD
	v_add3_u32 v25, v31, v25, s15
	v_add3_u32 v31, v33, v41, s15
	v_add3_u32 v32, v32, v44, s15
	v_add3_u32 v30, v30, v40, s15
	v_and_b32_e32 v31, 0xffff0000, v31
	v_and_b32_e32 v32, 0xffff0000, v32
	v_or_b32_sdwa v31, v31, v25 dst_sel:DWORD dst_unused:UNUSED_PAD src0_sel:DWORD src1_sel:WORD_1
	v_or_b32_sdwa v30, v32, v30 dst_sel:DWORD dst_unused:UNUSED_PAD src0_sel:DWORD src1_sel:WORD_1
	global_store_dwordx2 v[98:99], v[30:31], off offset:-1024
	ds_read_b128 v[30:33], v240 offset:6144
	s_waitcnt lgkmcnt(0)
	v_mov_b32_e32 v40, v30
	v_mov_b32_e32 v41, v32
	v_mov_b32_e32 v32, v31
	v_pk_mul_f32 v[30:31], v[66:67], v[40:41]
	v_pk_mul_f32 v[32:33], v[34:35], v[32:33]
	v_and_b32_sdwa v25, v31, v138 dst_sel:DWORD dst_unused:UNUSED_PAD src0_sel:WORD_1 src1_sel:DWORD
	v_and_b32_sdwa v35, v33, v138 dst_sel:DWORD dst_unused:UNUSED_PAD src0_sel:WORD_1 src1_sel:DWORD
	v_and_b32_sdwa v40, v32, v138 dst_sel:DWORD dst_unused:UNUSED_PAD src0_sel:WORD_1 src1_sel:DWORD
	v_and_b32_sdwa v34, v30, v138 dst_sel:DWORD dst_unused:UNUSED_PAD src0_sel:WORD_1 src1_sel:DWORD
	v_add3_u32 v25, v31, v25, s15
	v_add3_u32 v31, v33, v35, s15
	v_add3_u32 v32, v32, v40, s15
	v_add3_u32 v30, v30, v34, s15
	v_and_b32_e32 v31, 0xffff0000, v31
	v_and_b32_e32 v32, 0xffff0000, v32
	v_or_b32_sdwa v31, v31, v25 dst_sel:DWORD dst_unused:UNUSED_PAD src0_sel:DWORD src1_sel:WORD_1
	v_or_b32_sdwa v30, v32, v30 dst_sel:DWORD dst_unused:UNUSED_PAD src0_sel:DWORD src1_sel:WORD_1
	global_store_dwordx2 v[98:99], v[30:31], off offset:-512
	ds_read_b128 v[30:33], v240 offset:7168
	s_waitcnt lgkmcnt(0)
	v_mov_b32_e32 v34, v30
	v_mov_b32_e32 v35, v32
	v_mov_b32_e32 v32, v31
	v_pk_mul_f32 v[30:31], v[102:103], v[34:35]
	v_pk_mul_f32 v[32:33], v[38:39], v[32:33]
	v_and_b32_sdwa v25, v31, v138 dst_sel:DWORD dst_unused:UNUSED_PAD src0_sel:WORD_1 src1_sel:DWORD
	v_and_b32_sdwa v35, v33, v138 dst_sel:DWORD dst_unused:UNUSED_PAD src0_sel:WORD_1 src1_sel:DWORD
	v_and_b32_sdwa v38, v32, v138 dst_sel:DWORD dst_unused:UNUSED_PAD src0_sel:WORD_1 src1_sel:DWORD
	v_and_b32_sdwa v34, v30, v138 dst_sel:DWORD dst_unused:UNUSED_PAD src0_sel:WORD_1 src1_sel:DWORD
	v_add3_u32 v25, v31, v25, s15
	v_add3_u32 v31, v33, v35, s15
	v_add3_u32 v32, v32, v38, s15
	v_add3_u32 v30, v30, v34, s15
	v_and_b32_e32 v31, 0xffff0000, v31
	v_and_b32_e32 v32, 0xffff0000, v32
	v_or_b32_sdwa v31, v31, v25 dst_sel:DWORD dst_unused:UNUSED_PAD src0_sel:DWORD src1_sel:WORD_1
	v_or_b32_sdwa v30, v32, v30 dst_sel:DWORD dst_unused:UNUSED_PAD src0_sel:DWORD src1_sel:WORD_1
	global_store_dwordx2 v[94:95], v[30:31], off offset:-4096
	ds_read_b128 v[30:33], v240 offset:8192
	s_waitcnt lgkmcnt(0)
	v_mov_b32_e32 v34, v30
	v_mov_b32_e32 v35, v32
	v_mov_b32_e32 v32, v31
	v_pk_mul_f32 v[30:31], v[36:37], v[34:35]
	v_pk_mul_f32 v[32:33], v[42:43], v[32:33]
	v_and_b32_sdwa v25, v31, v138 dst_sel:DWORD dst_unused:UNUSED_PAD src0_sel:WORD_1 src1_sel:DWORD
	v_and_b32_sdwa v35, v33, v138 dst_sel:DWORD dst_unused:UNUSED_PAD src0_sel:WORD_1 src1_sel:DWORD
	v_and_b32_sdwa v36, v32, v138 dst_sel:DWORD dst_unused:UNUSED_PAD src0_sel:WORD_1 src1_sel:DWORD
	v_and_b32_sdwa v34, v30, v138 dst_sel:DWORD dst_unused:UNUSED_PAD src0_sel:WORD_1 src1_sel:DWORD
	v_add3_u32 v25, v31, v25, s15
	v_add3_u32 v31, v33, v35, s15
	v_add3_u32 v32, v32, v36, s15
	v_add3_u32 v30, v30, v34, s15
	v_and_b32_e32 v31, 0xffff0000, v31
	v_and_b32_e32 v32, 0xffff0000, v32
	v_or_b32_sdwa v31, v31, v25 dst_sel:DWORD dst_unused:UNUSED_PAD src0_sel:DWORD src1_sel:WORD_1
	v_or_b32_sdwa v30, v32, v30 dst_sel:DWORD dst_unused:UNUSED_PAD src0_sel:DWORD src1_sel:WORD_1
	global_store_dwordx2 v[94:95], v[30:31], off offset:-3584
	ds_read_b128 v[30:33], v240 offset:9216
	v_pk_mul_f32 v[26:27], v[26:27], v[24:25] op_sel_hi:[1,0]
	s_waitcnt lgkmcnt(0)
	v_mov_b32_e32 v35, v32
	v_mov_b32_e32 v32, v31
	v_mov_b32_e32 v34, v30
	v_pk_mul_f32 v[26:27], v[26:27], v[32:33]
	v_pk_mul_f32 v[28:29], v[28:29], v[34:35]
	v_and_b32_sdwa v31, v27, v138 dst_sel:DWORD dst_unused:UNUSED_PAD src0_sel:WORD_1 src1_sel:DWORD
	v_and_b32_sdwa v32, v26, v138 dst_sel:DWORD dst_unused:UNUSED_PAD src0_sel:WORD_1 src1_sel:DWORD
	v_and_b32_sdwa v25, v29, v138 dst_sel:DWORD dst_unused:UNUSED_PAD src0_sel:WORD_1 src1_sel:DWORD
	v_and_b32_sdwa v30, v28, v138 dst_sel:DWORD dst_unused:UNUSED_PAD src0_sel:WORD_1 src1_sel:DWORD
	v_add3_u32 v27, v27, v31, s15
	v_add3_u32 v26, v26, v32, s15
	v_add3_u32 v28, v28, v30, s15
	v_add3_u32 v25, v29, v25, s15
	v_and_b32_e32 v27, 0xffff0000, v27
	v_and_b32_e32 v26, 0xffff0000, v26
	v_or_b32_sdwa v27, v27, v25 dst_sel:DWORD dst_unused:UNUSED_PAD src0_sel:DWORD src1_sel:WORD_1
	v_or_b32_sdwa v26, v26, v28 dst_sel:DWORD dst_unused:UNUSED_PAD src0_sel:DWORD src1_sel:WORD_1
	global_store_dwordx2 v[94:95], v[26:27], off offset:-3072
	ds_read_b128 v[26:29], v240 offset:10240
	v_mov_b32_e32 v30, v20
	v_mov_b32_e32 v31, v22
	v_mov_b32_e32 v22, v21
	v_pk_mul_f32 v[20:21], v[30:31], v[24:25] op_sel_hi:[1,0]
	v_pk_mul_f32 v[22:23], v[22:23], v[24:25] op_sel_hi:[1,0]
	s_waitcnt lgkmcnt(0)
	v_mov_b32_e32 v31, v28
	v_mov_b32_e32 v28, v27
	v_mov_b32_e32 v30, v26
	v_pk_mul_f32 v[22:23], v[22:23], v[28:29]
	v_pk_mul_f32 v[20:21], v[20:21], v[30:31]
	v_and_b32_sdwa v27, v23, v138 dst_sel:DWORD dst_unused:UNUSED_PAD src0_sel:WORD_1 src1_sel:DWORD
	v_and_b32_sdwa v28, v22, v138 dst_sel:DWORD dst_unused:UNUSED_PAD src0_sel:WORD_1 src1_sel:DWORD
	v_and_b32_sdwa v25, v21, v138 dst_sel:DWORD dst_unused:UNUSED_PAD src0_sel:WORD_1 src1_sel:DWORD
	v_and_b32_sdwa v26, v20, v138 dst_sel:DWORD dst_unused:UNUSED_PAD src0_sel:WORD_1 src1_sel:DWORD
	v_add3_u32 v23, v23, v27, s15
	v_add3_u32 v22, v22, v28, s15
	v_add3_u32 v20, v20, v26, s15
	v_add3_u32 v21, v21, v25, s15
	v_and_b32_e32 v23, 0xffff0000, v23
	v_and_b32_e32 v22, 0xffff0000, v22
	v_or_b32_sdwa v21, v23, v21 dst_sel:DWORD dst_unused:UNUSED_PAD src0_sel:DWORD src1_sel:WORD_1
	v_or_b32_sdwa v20, v22, v20 dst_sel:DWORD dst_unused:UNUSED_PAD src0_sel:DWORD src1_sel:WORD_1
	global_store_dwordx2 v[94:95], v[20:21], off offset:-2560
	ds_read_b128 v[20:23], v240 offset:11264
	v_mov_b32_e32 v26, v16
	v_mov_b32_e32 v27, v18
	v_mov_b32_e32 v18, v17
	v_pk_mul_f32 v[16:17], v[26:27], v[24:25] op_sel_hi:[1,0]
	v_pk_mul_f32 v[18:19], v[18:19], v[24:25] op_sel_hi:[1,0]
	s_waitcnt lgkmcnt(0)
	v_mov_b32_e32 v27, v22
	v_mov_b32_e32 v22, v21
	v_mov_b32_e32 v26, v20
	v_pk_mul_f32 v[18:19], v[18:19], v[22:23]
	v_pk_mul_f32 v[16:17], v[16:17], v[26:27]
	v_and_b32_sdwa v22, v19, v138 dst_sel:DWORD dst_unused:UNUSED_PAD src0_sel:WORD_1 src1_sel:DWORD
	v_and_b32_sdwa v23, v18, v138 dst_sel:DWORD dst_unused:UNUSED_PAD src0_sel:WORD_1 src1_sel:DWORD
	v_and_b32_sdwa v20, v17, v138 dst_sel:DWORD dst_unused:UNUSED_PAD src0_sel:WORD_1 src1_sel:DWORD
	v_and_b32_sdwa v21, v16, v138 dst_sel:DWORD dst_unused:UNUSED_PAD src0_sel:WORD_1 src1_sel:DWORD
	v_add3_u32 v19, v19, v22, s15
	v_add3_u32 v18, v18, v23, s15
	v_add3_u32 v16, v16, v21, s15
	v_add3_u32 v17, v17, v20, s15
	v_and_b32_e32 v19, 0xffff0000, v19
	v_and_b32_e32 v18, 0xffff0000, v18
	v_or_b32_sdwa v17, v19, v17 dst_sel:DWORD dst_unused:UNUSED_PAD src0_sel:DWORD src1_sel:WORD_1
	v_or_b32_sdwa v16, v18, v16 dst_sel:DWORD dst_unused:UNUSED_PAD src0_sel:DWORD src1_sel:WORD_1
	global_store_dwordx2 v[94:95], v[16:17], off offset:-2048
	ds_read_b128 v[16:19], v240 offset:12288
	v_mov_b32_e32 v20, v12
	v_mov_b32_e32 v21, v14
	v_mov_b32_e32 v14, v13
	v_pk_mul_f32 v[12:13], v[20:21], v[24:25] op_sel_hi:[1,0]
	v_pk_mul_f32 v[14:15], v[14:15], v[24:25] op_sel_hi:[1,0]
	s_waitcnt lgkmcnt(0)
	v_mov_b32_e32 v21, v18
	v_mov_b32_e32 v18, v17
	v_mov_b32_e32 v20, v16
	v_pk_mul_f32 v[14:15], v[14:15], v[18:19]
	v_pk_mul_f32 v[12:13], v[12:13], v[20:21]
	v_and_b32_sdwa v18, v15, v138 dst_sel:DWORD dst_unused:UNUSED_PAD src0_sel:WORD_1 src1_sel:DWORD
	v_and_b32_sdwa v19, v14, v138 dst_sel:DWORD dst_unused:UNUSED_PAD src0_sel:WORD_1 src1_sel:DWORD
	v_and_b32_sdwa v16, v13, v138 dst_sel:DWORD dst_unused:UNUSED_PAD src0_sel:WORD_1 src1_sel:DWORD
	v_and_b32_sdwa v17, v12, v138 dst_sel:DWORD dst_unused:UNUSED_PAD src0_sel:WORD_1 src1_sel:DWORD
	v_add3_u32 v15, v15, v18, s15
	v_add3_u32 v14, v14, v19, s15
	v_add3_u32 v12, v12, v17, s15
	v_add3_u32 v13, v13, v16, s15
	v_and_b32_e32 v15, 0xffff0000, v15
	v_and_b32_e32 v14, 0xffff0000, v14
	v_or_b32_sdwa v13, v15, v13 dst_sel:DWORD dst_unused:UNUSED_PAD src0_sel:DWORD src1_sel:WORD_1
	v_or_b32_sdwa v12, v14, v12 dst_sel:DWORD dst_unused:UNUSED_PAD src0_sel:DWORD src1_sel:WORD_1
	global_store_dwordx2 v[94:95], v[12:13], off offset:-1536
	ds_read_b128 v[12:15], v240 offset:13312
	v_mov_b32_e32 v16, v8
	v_mov_b32_e32 v17, v10
	v_mov_b32_e32 v10, v9
	v_pk_mul_f32 v[8:9], v[16:17], v[24:25] op_sel_hi:[1,0]
	v_pk_mul_f32 v[10:11], v[10:11], v[24:25] op_sel_hi:[1,0]
	s_waitcnt lgkmcnt(0)
	v_mov_b32_e32 v17, v14
	v_mov_b32_e32 v14, v13
	v_mov_b32_e32 v16, v12
	v_pk_mul_f32 v[10:11], v[10:11], v[14:15]
	v_pk_mul_f32 v[8:9], v[8:9], v[16:17]
	v_and_b32_sdwa v14, v11, v138 dst_sel:DWORD dst_unused:UNUSED_PAD src0_sel:WORD_1 src1_sel:DWORD
	v_and_b32_sdwa v15, v10, v138 dst_sel:DWORD dst_unused:UNUSED_PAD src0_sel:WORD_1 src1_sel:DWORD
	v_and_b32_sdwa v12, v9, v138 dst_sel:DWORD dst_unused:UNUSED_PAD src0_sel:WORD_1 src1_sel:DWORD
	v_and_b32_sdwa v13, v8, v138 dst_sel:DWORD dst_unused:UNUSED_PAD src0_sel:WORD_1 src1_sel:DWORD
	v_add3_u32 v11, v11, v14, s15
	v_add3_u32 v10, v10, v15, s15
	v_add3_u32 v8, v8, v13, s15
	v_add3_u32 v9, v9, v12, s15
	v_and_b32_e32 v11, 0xffff0000, v11
	v_and_b32_e32 v10, 0xffff0000, v10
	v_or_b32_sdwa v9, v11, v9 dst_sel:DWORD dst_unused:UNUSED_PAD src0_sel:DWORD src1_sel:WORD_1
	v_or_b32_sdwa v8, v10, v8 dst_sel:DWORD dst_unused:UNUSED_PAD src0_sel:DWORD src1_sel:WORD_1
	global_store_dwordx2 v[94:95], v[8:9], off offset:-1024
	ds_read_b128 v[8:11], v240 offset:14336
	v_mov_b32_e32 v12, v4
	v_mov_b32_e32 v13, v6
	v_mov_b32_e32 v6, v5
	v_pk_mul_f32 v[4:5], v[12:13], v[24:25] op_sel_hi:[1,0]
	v_pk_mul_f32 v[6:7], v[6:7], v[24:25] op_sel_hi:[1,0]
	s_waitcnt lgkmcnt(0)
	v_mov_b32_e32 v13, v10
	v_mov_b32_e32 v10, v9
	v_mov_b32_e32 v12, v8
	v_pk_mul_f32 v[6:7], v[6:7], v[10:11]
	v_pk_mul_f32 v[4:5], v[4:5], v[12:13]
	v_and_b32_sdwa v10, v7, v138 dst_sel:DWORD dst_unused:UNUSED_PAD src0_sel:WORD_1 src1_sel:DWORD
	v_and_b32_sdwa v11, v6, v138 dst_sel:DWORD dst_unused:UNUSED_PAD src0_sel:WORD_1 src1_sel:DWORD
	v_and_b32_sdwa v8, v5, v138 dst_sel:DWORD dst_unused:UNUSED_PAD src0_sel:WORD_1 src1_sel:DWORD
	v_and_b32_sdwa v9, v4, v138 dst_sel:DWORD dst_unused:UNUSED_PAD src0_sel:WORD_1 src1_sel:DWORD
	v_add3_u32 v7, v7, v10, s15
	v_add3_u32 v6, v6, v11, s15
	v_add3_u32 v4, v4, v9, s15
	v_add3_u32 v5, v5, v8, s15
	v_and_b32_e32 v7, 0xffff0000, v7
	v_and_b32_e32 v6, 0xffff0000, v6
	v_or_b32_sdwa v5, v7, v5 dst_sel:DWORD dst_unused:UNUSED_PAD src0_sel:DWORD src1_sel:WORD_1
	v_or_b32_sdwa v4, v6, v4 dst_sel:DWORD dst_unused:UNUSED_PAD src0_sel:DWORD src1_sel:WORD_1
	global_store_dwordx2 v[94:95], v[4:5], off offset:-512
	ds_read_b128 v[4:7], v240 offset:15360
	v_mov_b32_e32 v8, v0
	v_mov_b32_e32 v9, v2
	v_mov_b32_e32 v2, v1
	v_pk_mul_f32 v[0:1], v[8:9], v[24:25] op_sel_hi:[1,0]
	v_pk_mul_f32 v[2:3], v[2:3], v[24:25] op_sel_hi:[1,0]
	s_waitcnt lgkmcnt(0)
	v_mov_b32_e32 v9, v6
	v_mov_b32_e32 v6, v5
	v_mov_b32_e32 v8, v4
	v_pk_mul_f32 v[2:3], v[2:3], v[6:7]
	v_pk_mul_f32 v[0:1], v[0:1], v[8:9]
	v_and_b32_sdwa v6, v3, v138 dst_sel:DWORD dst_unused:UNUSED_PAD src0_sel:WORD_1 src1_sel:DWORD
	v_and_b32_sdwa v7, v2, v138 dst_sel:DWORD dst_unused:UNUSED_PAD src0_sel:WORD_1 src1_sel:DWORD
	v_and_b32_sdwa v4, v1, v138 dst_sel:DWORD dst_unused:UNUSED_PAD src0_sel:WORD_1 src1_sel:DWORD
	v_and_b32_sdwa v5, v0, v138 dst_sel:DWORD dst_unused:UNUSED_PAD src0_sel:WORD_1 src1_sel:DWORD
	v_add3_u32 v3, v3, v6, s15
	v_add3_u32 v2, v2, v7, s15
	v_add3_u32 v0, v0, v5, s15
	v_add3_u32 v1, v1, v4, s15
	v_and_b32_e32 v3, 0xffff0000, v3
	v_and_b32_e32 v2, 0xffff0000, v2
	v_or_b32_sdwa v1, v3, v1 dst_sel:DWORD dst_unused:UNUSED_PAD src0_sel:DWORD src1_sel:WORD_1
	v_or_b32_sdwa v0, v2, v0 dst_sel:DWORD dst_unused:UNUSED_PAD src0_sel:DWORD src1_sel:WORD_1
	global_store_dwordx2 v[94:95], v[0:1], off
	v_lshl_add_u64 v[94:95], v[94:95], 0, s[6:7]
	s_cbranch_scc1 .LBB0_367
